# attention: counted lgkmcnt waits; Q fragments via global loads so the unit prologue no longer drains the K/V prefetch
# speedup vs baseline: 1.0400x; 1.0015x over previous
; #define MFMA(a, b, c) __builtin_amdgcn_mfma_f32_32x32x16_bf16((a), (b), (c), 0, 0, 0)
; DI bf16x8 ldfrag(const char* lds, int row, int chunk) { return *(const bf16x8*)(lds + swz(row, chunk)); }
; DI void attn_phase(const bf16_t* __restrict__ qb, const bf16_t* __restrict__ kb, const bf16_t* __restrict__ vt, bf16_t* __restrict__ ob, ...
;     ...
;         const long qrow_t = t0 + qblk * 128 + qs * 32 + l31;
;         bf16x8 qf[4];
;         {
;             const bf16_t* qrow = qb + qrow_t * 1024 + (head * 2 + c) * 64 + 8 * hh;
; #pragma unroll
;             for (int s = 0; s < 4; ++s) qf[s] = *(const bf16x8*)(qrow + 16 * s);
;         }
;         const int cl = sch ^ ((srow >> 1) & 7);
;         const bf16_t* kp = kb + (t0 + srow) * 1024 + head * 128 + cl * 8;
;         const bf16_t* vp = vt + t0 * 1024 + ((long)head * 128 + srow) * S + cl * 8;
;         const int nkt = S / 64;
;     ...
;         ATT_ISSUE(0, 0); ATT_ISSUE(1, 1); ATT_ISSUE(2, 2);
;         f32x16 oacc[4];
; #pragma unroll
;         for (int ef = 0; ef < 4; ++ef)
; #pragma unroll
;             for (int i = 0; i < 16; ++i) oacc[ef][i] = 0.f;
;         float l_run = 0.f;
;         f32x16 negm;
; #pragma unroll
;         for (int i = 0; i < 16; ++i) negm[i] = 0.f;
;         for (int kt = 0; kt < nkt; ++kt) {
;             asm volatile("s_waitcnt vmcnt(8)" ::: "memory");
;             asm volatile("s_waitcnt lgkmcnt(0)" ::: "memory"); __builtin_amdgcn_s_barrier();
;             ATT_ISSUE(kt + 3, (kt + 3) & 3);
;             const char* cur = lds + (kt & 3) * 32768;
;             const char* kl = cur + c * 8192; const char* vl = cur + 16384;
;             f32x16 sacc[2];
;             {
;                 bf16x8 kfr[2][4];
; #pragma unroll
;                 for (int kf = 0; kf < 2; ++kf)
; #pragma unroll
;                     for (int s = 0; s < 4; ++s) kfr[kf][s] = ldfrag(kl, kf * 32 + l31, 2 * s + hh);
; #pragma unroll
;                 for (int kf = 0; kf < 2; ++kf) {
;                     sacc[kf] = MFMA(kfr[kf][0], qf[0], negm);
; #pragma unroll
;                     for (int s = 1; s < 4; ++s) sacc[kf] = MFMA(kfr[kf][s], qf[s], sacc[kf]);
;                 }
.LBB0_213:
	s_and_b64 s[8:9], s[20:21], exec
	s_cselect_b32 s19, s46, 0x2000
	s_lshl_b32 s8, s38, 7
	s_add_u32 s8, s16, s8
	s_addc_u32 s9, s17, 0
	v_lshl_add_u64 v[0:1], s[8:9], 0, v[152:153]
	s_lshl_b32 s8, s37, 7
	s_and_b32 s8, s8, 0x380
	v_lshlrev_b64 v[162:163], 10, v[0:1]
	v_lshlrev_b64 v[0:1], 11, v[0:1]
	v_or_b32_e32 v2, s8, v191
	v_lshl_add_u64 v[0:1], s[70:71], 0, v[0:1]
	v_lshlrev_b32_e32 v146, 1, v2
	v_lshl_add_u64 v[0:1], v[0:1], 0, v[146:147]
	v_mov_b32_e32 v157, v147
	v_lshl_add_u64 v[0:1], v[0:1], 0, v[156:157]
	v_mov_b32_e32 v204, 0
	v_mov_b32_e32 v205, 0
	v_mov_b32_e32 v206, 0
	v_mov_b32_e32 v207, 0
	v_mov_b32_e32 v208, 0
	v_mov_b32_e32 v209, 0
	v_mov_b32_e32 v210, 0
	v_mov_b32_e32 v211, 0
	v_mov_b32_e32 v212, 0
	v_mov_b32_e32 v213, 0
	v_mov_b32_e32 v214, 0
	v_mov_b32_e32 v215, 0
	v_mov_b32_e32 v216, 0
	v_mov_b32_e32 v217, 0
	v_mov_b32_e32 v218, 0
	v_mov_b32_e32 v219, 0
	v_mov_b32_e32 v220, 0
	v_mov_b32_e32 v221, 0
	v_mov_b32_e32 v222, 0
	v_mov_b32_e32 v223, 0
	global_load_dwordx4 v[114:117], v[0:1], off
	global_load_dwordx4 v[118:121], v[0:1], off offset:32
	global_load_dwordx4 v[122:125], v[0:1], off offset:64
	global_load_dwordx4 v[126:129], v[0:1], off offset:96
	v_lshl_add_u64 v[0:1], s[16:17], 0, v[150:151]
	v_lshlrev_b64 v[0:1], 11, v[0:1]
	v_lshl_add_u64 v[0:1], s[22:23], 0, v[0:1]
	s_lshl_b32 s86, s8, 1
	s_mov_b32 s9, s87
	v_lshl_add_u64 v[0:1], v[0:1], 0, s[86:87]
	v_mov_b32_e32 v159, v147
	s_lshl_b64 s[16:17], s[16:17], 11
	v_lshl_add_u64 v[164:165], v[0:1], 0, v[158:159]
	s_add_u32 s16, s47, s16
	v_lshl_add_u64 v[0:1], s[8:9], 0, v[150:151]
	s_addc_u32 s17, s48, s17
	v_lshlrev_b64 v[0:1], s18, v[0:1]
	s_mov_b32 m0, s30
	v_lshl_add_u64 v[0:1], v[0:1], 1, s[16:17]
	v_lshl_add_u64 v[166:167], v[0:1], 0, v[158:159]
	global_load_lds_dwordx4 v[164:165], off
	v_lshl_add_u64 v[0:1], v[164:165], 0, s[14:15]
	s_add_i32 m0, s30, 0x2000
	s_lshl_b32 s86, s19, 7
	global_load_lds_dwordx4 v[0:1], off
	s_add_i32 m0, s30, 0x4000
	v_lshl_add_u64 v[0:1], v[166:167], 0, s[86:87]
	global_load_lds_dwordx4 v[166:167], off
	s_add_i32 m0, s30, 0x6000
	v_add_u32_e32 v40, v196, v198
	global_load_lds_dwordx4 v[0:1], off
	v_lshl_add_u64 v[2:3], v[164:165], 0, s[88:89]
	s_add_i32 m0, s30, 0x8000
	v_lshl_add_u64 v[4:5], v[166:167], 0, s[14:15]
	global_load_lds_dwordx4 v[2:3], off
	v_lshl_add_u64 v[2:3], v[164:165], 0, s[72:73]
	s_add_i32 m0, s30, 0xa000
	v_add_u32_e32 v99, v196, v199
	global_load_lds_dwordx4 v[2:3], off
	s_add_i32 m0, s30, 0xc000
	v_lshl_add_u64 v[2:3], v[0:1], 0, s[14:15]
	global_load_lds_dwordx4 v[4:5], off
	s_add_i32 m0, s30, 0xe000
	v_lshl_add_u64 v[4:5], v[166:167], 0, s[74:75]
	global_load_lds_dwordx4 v[2:3], off
	v_lshl_add_u64 v[2:3], v[164:165], 0, s[90:91]
	s_add_i32 m0, s30, 0x10000
	v_add_u32_e32 v142, v196, v200
	global_load_lds_dwordx4 v[2:3], off
	v_lshl_add_u64 v[2:3], v[164:165], 0, s[76:77]
	s_add_i32 m0, s30, 0x12000
	s_lshr_b32 s9, s19, 6
	global_load_lds_dwordx4 v[2:3], off
	s_add_i32 m0, s30, 0x14000
	v_lshl_add_u64 v[2:3], v[0:1], 0, s[74:75]
	global_load_lds_dwordx4 v[4:5], off
	s_add_i32 m0, s30, 0x16000
	v_lshl_add_u64 v[4:5], v[166:167], 0, s[42:43]
	global_load_lds_dwordx4 v[2:3], off
	s_waitcnt vmcnt(8)
	v_lshl_add_u64 v[2:3], v[164:165], 0, s[92:93]
	s_mov_b32 m0, s31
	s_waitcnt lgkmcnt(0)
	s_barrier
	global_load_lds_dwordx4 v[2:3], off
	v_lshl_add_u64 v[2:3], v[164:165], 0, s[0:1]
	s_mov_b32 m0, s34
	v_lshl_add_u64 v[0:1], v[0:1], 0, s[42:43]
	global_load_lds_dwordx4 v[2:3], off
	s_mov_b32 m0, s35
	s_lshl_b32 s16, s19, 6
	global_load_lds_dwordx4 v[4:5], off
	s_mov_b32 m0, s36
	s_add_i32 s9, s9, -1
	global_load_lds_dwordx4 v[0:1], off
	ds_read_b128 v[32:35], v202 offset:24576
	ds_read_b128 v[36:39], v40 offset:20480
	v_add_u32_e32 v24, v197, v198
	ds_read_b128 v[0:3], v24 offset:4096
	ds_read_b128 v[24:27], v24
	v_add_u32_e32 v8, v197, v194
	v_add_u32_e32 v9, v197, v200
	v_add_u32_e32 v28, v197, v199
	ds_read_b128 v[4:7], v8 offset:4096
	s_waitcnt lgkmcnt(0)
	v_mfma_f32_32x32x16_bf16 v[50:65], v[4:7], v[114:117], 0
	ds_read_b128 v[16:19], v9
	ds_read_b128 v[100:103], v40 offset:28672
	ds_read_b128 v[82:85], v99 offset:20480
	ds_read_b128 v[78:81], v99 offset:16384
	s_mov_b32 s18, 0
	s_mov_b32 s19, 0x20000
	s_lshl_b32 s16, s16, 1
	v_mfma_f32_32x32x16_bf16 v[50:65], v[0:3], v[118:121], v[50:65]
	ds_read_b128 v[20:23], v9 offset:4096
	ds_read_b128 v[0:3], v28 offset:4096
	s_waitcnt lgkmcnt(0)
	v_mfma_f32_32x32x16_bf16 v[50:65], v[0:3], v[122:125], v[50:65]
	ds_read_b128 v[0:3], v8
	s_waitcnt lgkmcnt(0)
	v_mfma_f32_32x32x16_bf16 v[0:15], v[0:3], v[114:117], 0
	v_mfma_f32_32x32x16_bf16 v[0:15], v[24:27], v[118:121], v[0:15]
	ds_read_b128 v[24:27], v28
	v_mfma_f32_32x32x16_bf16 v[50:65], v[20:23], v[126:129], v[50:65]
	s_waitcnt lgkmcnt(0)
	v_mfma_f32_32x32x16_bf16 v[0:15], v[24:27], v[122:125], v[0:15]
	v_mfma_f32_32x32x16_bf16 v[0:15], v[16:19], v[126:129], v[0:15]
	s_nop 11
	v_max_f32_e32 v16, v1, v1
	v_max_f32_e32 v17, v0, v0
	v_max_f32_e32 v16, v17, v16
	v_max3_f32 v16, v16, v2, v3
	v_max3_f32 v16, v16, v4, v5
	v_max3_f32 v16, v16, v6, v7
	v_max3_f32 v16, v16, v8, v9
	v_max3_f32 v16, v16, v10, v11
	v_max3_f32 v16, v16, v12, v13
	v_max3_f32 v16, v16, v14, v15
	v_max3_f32 v16, v16, v50, v51
	v_max3_f32 v16, v16, v52, v53
	v_max3_f32 v16, v16, v54, v55
	v_max3_f32 v16, v16, v56, v57
	v_max3_f32 v16, v16, v58, v59
	v_max3_f32 v16, v16, v60, v61
	v_max3_f32 v16, v16, v62, v63
	v_max3_f32 v16, v16, v64, v65
	ds_bpermute_b32 v17, v190, v16
	s_waitcnt lgkmcnt(0)
; #define MFMA(a, b, c) __builtin_amdgcn_mfma_f32_32x32x16_bf16((a), (b), (c), 0, 0, 0)
; DI bf16x8 ldfrag(const char* lds, int row, int chunk) { return *(const bf16x8*)(lds + swz(row, chunk)); }
; DI void attn_phase(const bf16_t* __restrict__ qb, const bf16_t* __restrict__ kb, const bf16_t* __restrict__ vt, bf16_t* __restrict__ ob, ...
;     ...
;             float mx = fmaxf(fmaxf(sacc[0][0], sacc[0][1]), sacc[0][2]);
; #pragma unroll
;             for (int i = 3; i < 15; i += 2) mx = fmaxf(fmaxf(mx, sacc[0][i]), sacc[0][i + 1]);
;             mx = fmaxf(fmaxf(mx, sacc[0][15]), sacc[1][0]);
; #pragma unroll
;             for (int i = 1; i < 15; i += 2) mx = fmaxf(fmaxf(mx, sacc[1][i]), sacc[1][i + 1]);
;             mx = fmaxf(mx, sacc[1][15]);
;             if (kt == 0 || __any(mx > 8.0f)) {
;                 const float mfull = fmaxf(mx, __shfl_xor(mx, 32));
;                 const float delta = kt == 0 ? mfull : fmaxf(mfull, 0.f);
;                 const float alpha = kt == 0 ? 1.0f : __builtin_amdgcn_exp2f(-delta);
;                 l_run *= alpha;
; #pragma unroll
;                 for (int ef = 0; ef < 4; ++ef)
; #pragma unroll
;                     for (int i = 0; i < 16; ++i) oacc[ef][i] *= alpha;
; #pragma unroll
;                 for (int i = 0; i < 16; ++i) { negm[i] -= delta; sacc[0][i] -= delta; sacc[1][i] -= delta; }
;             }
;             float ps = 0.f;
;             bf16x8 pq[4];
;     ...
;             ATT_SOFTQ(0);
; #pragma unroll
;             for (int q = 0; q < 4; ++q) {
;                 if (q < 3) {
; #pragma unroll
;                     for (int ef = 0; ef < 4; ++ef) vf[(q + 1) & 1][ef] = ldfrag(vl, ef * 32 + l31, ((q + 1) >> 1) * 4 + 2 * ((q + 1) & 1) + hh);
;                     if (q == 0) ATT_SOFTQ(1); else if (q == 1) ATT_SOFTQ(2); else ATT_SOFTQ(3);
;                 }
; #pragma unroll
;                 for (int ef = 0; ef < 4; ++ef) oacc[ef] = MFMA(vf[q & 1][ef], pq[q], oacc[ef]);
;             }
;             l_run += ps;
	v_max_f32_e32 v17, v17, v17
	v_max_f32_e32 v93, v16, v17
	v_sub_f32_e32 v104, v50, v93
	v_sub_f32_e32 v105, v51, v93
	ds_read_b128 v[48:51], v202 offset:28672
	v_sub_f32_e32 v6, v6, v93
	v_sub_f32_e32 v7, v7, v93
	v_sub_f32_e32 v1, v1, v93
	v_sub_f32_e32 v2, v2, v93
	v_sub_f32_e32 v3, v3, v93
	v_sub_f32_e32 v4, v4, v93
	v_sub_f32_e32 v5, v5, v93
	v_sub_f32_e32 v0, v0, v93
	v_exp_f32_e32 v94, v0
	v_exp_f32_e32 v95, v1
	v_exp_f32_e32 v96, v2
	v_exp_f32_e32 v97, v3
	v_exp_f32_e32 v98, v4
	v_exp_f32_e32 v87, v5
	v_exp_f32_e32 v88, v6
	v_exp_f32_e32 v89, v7
	v_cvt_pk_bf16_f32 v66, v94, v95
	v_cvt_pk_bf16_f32 v67, v96, v97
	v_cvt_pk_bf16_f32 v68, v98, v87
	v_cvt_pk_bf16_f32 v69, v88, v89
	v_sub_f32_e32 v52, v52, v93
	v_sub_f32_e32 v53, v53, v93
	v_sub_f32_e32 v106, v54, v93
	v_sub_f32_e32 v107, v55, v93
	v_sub_f32_e32 v112, v56, v93
	v_sub_f32_e32 v113, v57, v93
	v_sub_f32_e32 v130, v58, v93
	v_sub_f32_e32 v131, v59, v93
	v_sub_f32_e32 v132, v60, v93
	v_sub_f32_e32 v133, v61, v93
	v_sub_f32_e32 v134, v62, v93
	v_sub_f32_e32 v135, v63, v93
	v_exp_f32_e32 v138, v52
	v_exp_f32_e32 v139, v53
	s_waitcnt lgkmcnt(0)
	v_mfma_f32_32x32x16_bf16 v[48:63], v[48:51], v[66:69], 0
	v_sub_f32_e32 v8, v8, v93
	v_sub_f32_e32 v9, v9, v93
	v_sub_f32_e32 v10, v10, v93
	v_sub_f32_e32 v11, v11, v93
	v_sub_f32_e32 v16, v12, v93
	v_sub_f32_e32 v17, v13, v93
	v_sub_f32_e32 v18, v14, v93
	v_sub_f32_e32 v19, v15, v93
	v_exp_f32_e32 v90, v8
	v_exp_f32_e32 v91, v9
	v_exp_f32_e32 v92, v10
	v_exp_f32_e32 v86, v11
	v_exp_f32_e32 v108, v16
	v_exp_f32_e32 v109, v17
	v_exp_f32_e32 v110, v18
	v_exp_f32_e32 v111, v19
	v_cvt_pk_bf16_f32 v70, v90, v91
	v_cvt_pk_bf16_f32 v71, v92, v86
	v_cvt_pk_bf16_f32 v72, v108, v109
	v_cvt_pk_bf16_f32 v73, v110, v111
	v_exp_f32_e32 v136, v104
	v_exp_f32_e32 v137, v105
	v_mfma_f32_32x32x16_bf16 v[48:63], v[100:103], v[70:73], v[48:63]
	ds_read_b128 v[74:77], v40 offset:24576
	ds_read_b128 v[16:19], v202 offset:20480
	ds_read_b128 v[20:23], v202 offset:16384
	v_exp_f32_e32 v140, v106
	v_exp_f32_e32 v141, v107
	v_exp_f32_e32 v112, v112
	v_exp_f32_e32 v113, v113
	s_waitcnt lgkmcnt(0)
	v_mfma_f32_32x32x16_bf16 v[0:15], v[20:23], v[66:69], 0
	ds_read_b128 v[20:23], v40 offset:16384
	v_cvt_pk_bf16_f32 v104, v136, v137
	v_cvt_pk_bf16_f32 v105, v138, v139
	v_cvt_pk_bf16_f32 v106, v140, v141
	v_cvt_pk_bf16_f32 v107, v112, v113
	v_sub_f32_e32 v64, v64, v93
	v_sub_f32_e32 v65, v65, v93
	s_waitcnt lgkmcnt(0)
	v_mfma_f32_32x32x16_bf16 v[0:15], v[20:23], v[70:73], v[0:15]
	ds_read_b128 v[100:103], v99 offset:24576
	v_exp_f32_e32 v64, v64
	v_exp_f32_e32 v65, v65
	v_mfma_f32_32x32x16_bf16 v[16:31], v[16:19], v[66:69], 0
	v_mfma_f32_32x32x16_bf16 v[16:31], v[36:39], v[70:73], v[16:31]
	v_mfma_f32_32x32x16_bf16 v[32:47], v[32:35], v[66:69], 0
	v_sub_f32_e32 v66, 0, v93
	v_mov_b32_e32 v67, v66
	v_mov_b32_e32 v68, v66
	v_mov_b32_e32 v69, v66
	v_mfma_f32_32x32x16_bf16 v[16:31], v[82:85], v[104:107], v[16:31]
	v_add_f32_e32 v82, 0, v94
	v_add_f32_e32 v82, v95, v82
	v_add_f32_e32 v82, v96, v82
	v_add_f32_e32 v82, v97, v82
	v_add_f32_e32 v93, v98, v82
	ds_read_b128 v[82:85], v99 offset:28672
	v_add_f32_e32 v87, v87, v93
	v_mfma_f32_32x32x16_bf16 v[32:47], v[74:77], v[70:73], v[32:47]
	ds_read_b128 v[94:97], v142 offset:16384
	v_add_f32_e32 v87, v88, v87
	v_add_f32_e32 v87, v89, v87
	v_add_f32_e32 v87, v90, v87
	v_add_f32_e32 v87, v91, v87
	v_add_f32_e32 v87, v92, v87
	v_add_f32_e32 v86, v86, v87
	v_mfma_f32_32x32x16_bf16 v[0:15], v[78:81], v[104:107], v[0:15]
	v_add_f32_e32 v86, v108, v86
	v_add_f32_e32 v86, v109, v86
	v_add_f32_e32 v86, v110, v86
	ds_read_b128 v[88:91], v142 offset:24576
	v_add_f32_e32 v86, v111, v86
	v_add_f32_e32 v86, v136, v86
	v_add_f32_e32 v86, v137, v86
	s_waitcnt lgkmcnt(3)
	v_mfma_f32_32x32x16_bf16 v[32:47], v[100:103], v[104:107], v[32:47]
	v_exp_f32_e32 v102, v130
	v_exp_f32_e32 v103, v131
	v_exp_f32_e32 v130, v132
	v_exp_f32_e32 v131, v133
	v_exp_f32_e32 v132, v134
	ds_read_b128 v[98:101], v142 offset:20480
	v_add_f32_e32 v86, v138, v86
	s_waitcnt lgkmcnt(3)
	v_mfma_f32_32x32x16_bf16 v[48:63], v[82:85], v[104:107], v[48:63]
	v_exp_f32_e32 v104, v135
	v_cvt_pk_bf16_f32 v82, v102, v103
	v_cvt_pk_bf16_f32 v83, v130, v131
	v_cvt_pk_bf16_f32 v85, v64, v65
	v_cvt_pk_bf16_f32 v84, v132, v104
	v_add_f32_e32 v86, v139, v86
	v_add_f32_e32 v86, v140, v86
	s_waitcnt lgkmcnt(2)
	v_mfma_f32_32x32x16_bf16 v[0:15], v[94:97], v[82:85], v[0:15]
	ds_read_b128 v[92:95], v142 offset:28672
	v_add_f32_e32 v86, v141, v86
	v_add_f32_e32 v86, v112, v86
	v_add_f32_e32 v86, v113, v86
	v_mov_b32_e32 v70, v66
	v_mov_b32_e32 v71, v66
	v_mov_b32_e32 v72, v66
	s_waitcnt lgkmcnt(1)
	v_mfma_f32_32x32x16_bf16 v[16:31], v[98:101], v[82:85], v[16:31]
	v_mov_b32_e32 v73, v66
	v_mov_b32_e32 v74, v66
	v_mov_b32_e32 v75, v66
	v_mov_b32_e32 v76, v66
	v_mov_b32_e32 v77, v66
	v_mov_b32_e32 v78, v66
	v_mov_b32_e32 v79, v66
	v_mfma_f32_32x32x16_bf16 v[32:47], v[88:91], v[82:85], v[32:47]
	v_mov_b32_e32 v80, v66
	v_mov_b32_e32 v81, v66
	s_waitcnt lgkmcnt(0)
	v_mfma_f32_32x32x16_bf16 v[48:63], v[92:95], v[82:85], v[48:63]
	v_add_f32_e32 v82, v102, v86
	v_add_f32_e32 v82, v103, v82
	v_add_f32_e32 v82, v130, v82
	v_add_f32_e32 v82, v131, v82
	v_add_f32_e32 v82, v132, v82
	v_add_f32_e32 v82, v104, v82
	v_add_f32_e32 v64, v64, v82
	v_add_f32_e32 v64, v65, v64
	v_add_f32_e32 v64, 0, v64
	s_branch .LBB0_215
; #define MFMA(a, b, c) __builtin_amdgcn_mfma_f32_32x32x16_bf16((a), (b), (c), 0, 0, 0)
; DI bf16x8 ldfrag(const char* lds, int row, int chunk) { return *(const bf16x8*)(lds + swz(row, chunk)); }
; DI void attn_phase(const bf16_t* __restrict__ qb, const bf16_t* __restrict__ kb, const bf16_t* __restrict__ vt, bf16_t* __restrict__ ob, ...
;     ...
;             float ps = 0.f;
;             bf16x8 pq[4];
;     ...
;             ATT_SOFTQ(0);
; #pragma unroll
;             for (int q = 0; q < 4; ++q) {
;                 if (q < 3) {
; #pragma unroll
;                     for (int ef = 0; ef < 4; ++ef) vf[(q + 1) & 1][ef] = ldfrag(vl, ef * 32 + l31, ((q + 1) >> 1) * 4 + 2 * ((q + 1) & 1) + hh);
;                     if (q == 0) ATT_SOFTQ(1); else if (q == 1) ATT_SOFTQ(2); else ATT_SOFTQ(3);
;                 }
; #pragma unroll
;                 for (int ef = 0; ef < 4; ++ef) oacc[ef] = MFMA(vf[q & 1][ef], pq[q], oacc[ef]);
;             }
;             l_run += ps;
;             __builtin_amdgcn_sched_group_barrier(0x002, 20, 0);
; #pragma unroll
;             for (int g_ = 0; g_ < 12; ++g_) { __builtin_amdgcn_sched_group_barrier(0x008, 1, 0); __builtin_amdgcn_sched_group_barrier(0x100, 1, 0); __builtin_amdgcn_sched_group_barrier(0x002, 5, 0); }
;             __builtin_amdgcn_sched_group_barrier(0x008, 4, 0);
.LBB0_214:
	v_exp_f32_e32 v65, v98
	v_exp_f32_e32 v98, v99
	v_exp_f32_e32 v99, v100
	v_exp_f32_e32 v100, v101
	v_add_f32_e32 v101, 0, v65
	v_exp_f32_e32 v102, v102
	v_add_f32_e32 v101, v98, v101
	v_exp_f32_e32 v103, v103
	v_add_f32_e32 v101, v99, v101
	v_exp_f32_e32 v104, v104
	v_add_f32_e32 v101, v100, v101
	v_exp_f32_e32 v105, v105
	v_add_f32_e32 v101, v102, v101
	v_exp_f32_e32 v106, v106
	v_exp_f32_e32 v107, v107
	v_add_f32_e32 v101, v103, v101
	v_add_f32_e32 v101, v104, v101
	v_exp_f32_e32 v159, v108
	v_exp_f32_e32 v161, v109
	v_exp_f32_e32 v110, v110
	v_exp_f32_e32 v111, v111
	v_exp_f32_e32 v112, v112
	v_exp_f32_e32 v172, v113
	v_add_f32_e32 v146, v105, v101
	v_cvt_pk_bf16_f32 v98, v65, v98
	v_cvt_pk_bf16_f32 v99, v99, v100
	v_cvt_pk_bf16_f32 v100, v102, v103
	v_add_u32_e32 v65, s17, v193
	v_cvt_pk_bf16_f32 v102, v106, v107
	v_add_f32_e32 v106, v106, v146
	v_cvt_pk_bf16_f32 v101, v104, v105
	v_add_u32_e32 v157, v65, v198
	v_add_f32_e32 v113, v107, v106
	v_cvt_pk_bf16_f32 v103, v159, v161
	v_cvt_pk_bf16_f32 v104, v110, v111
	v_cvt_pk_bf16_f32 v105, v112, v172
	s_waitcnt lgkmcnt(3)
	v_mfma_f32_32x32x16_bf16 v[0:15], v[142:145], v[98:101], v[0:15]
	ds_read_b128 v[106:109], v157 offset:16384
	v_add_f32_e32 v113, v159, v113
	v_add_f32_e32 v113, v161, v113
	v_add_f32_e32 v110, v110, v113
	v_add_f32_e32 v110, v111, v110
	v_add_f32_e32 v142, v112, v110
	v_exp_f32_e32 v143, v86
	s_waitcnt lgkmcnt(3)
	v_mfma_f32_32x32x16_bf16 v[16:31], v[138:141], v[98:101], v[16:31]
	ds_read_b128 v[110:113], v157 offset:20480
	v_add_f32_e32 v138, v172, v142
	v_exp_f32_e32 v139, v82
	v_exp_f32_e32 v140, v83
	v_exp_f32_e32 v141, v84
	v_exp_f32_e32 v142, v85
	v_exp_f32_e32 v144, v87
	v_add_u32_e32 v145, v65, v199
	v_cvt_pk_bf16_f32 v82, v139, v140
	v_cvt_pk_bf16_f32 v83, v141, v142
	v_cvt_pk_bf16_f32 v84, v143, v144
	s_waitcnt lgkmcnt(3)
	v_mfma_f32_32x32x16_bf16 v[32:47], v[134:137], v[98:101], v[32:47]
	v_exp_f32_e32 v134, v88
	v_exp_f32_e32 v135, v89
	ds_read_b128 v[86:89], v157 offset:24576
	v_add_f32_e32 v136, v139, v138
	v_add_f32_e32 v136, v140, v136
	v_add_f32_e32 v136, v141, v136
	v_add_f32_e32 v136, v142, v136
	v_cvt_pk_bf16_f32 v85, v134, v135
	s_waitcnt lgkmcnt(3)
	v_mfma_f32_32x32x16_bf16 v[48:63], v[130:133], v[98:101], v[48:63]
	ds_read_b128 v[98:101], v157 offset:28672
	v_add_f32_e32 v130, v143, v136
	v_add_f32_e32 v130, v144, v130
	v_add_f32_e32 v130, v134, v130
	v_exp_f32_e32 v131, v90
	v_add_f32_e32 v130, v135, v130
	v_exp_f32_e32 v132, v91
	v_exp_f32_e32 v133, v92
	v_exp_f32_e32 v134, v93
	v_exp_f32_e32 v135, v94
	v_exp_f32_e32 v136, v95
	v_exp_f32_e32 v137, v96
	v_exp_f32_e32 v138, v97
	v_add_u32_e32 v65, v65, v200
	s_waitcnt lgkmcnt(3)
	v_mfma_f32_32x32x16_bf16 v[0:15], v[106:109], v[102:105], v[0:15]
	ds_read_b128 v[106:109], v145 offset:16384
	v_add_f32_e32 v130, v131, v130
	v_cvt_pk_bf16_f32 v220, v131, v132
	v_cvt_pk_bf16_f32 v221, v133, v134
	v_cvt_pk_bf16_f32 v222, v135, v136
	v_cvt_pk_bf16_f32 v223, v137, v138
	s_add_i32 s18, s18, 1
	s_waitcnt lgkmcnt(3)
	v_mfma_f32_32x32x16_bf16 v[16:31], v[110:113], v[102:105], v[16:31]
	ds_read_b128 v[94:97], v145 offset:20480
	v_add_f32_e32 v110, v132, v130
	v_add_f32_e32 v110, v133, v110
	v_add_f32_e32 v110, v134, v110
	v_add_f32_e32 v110, v135, v110
	v_add_f32_e32 v110, v136, v110
	s_add_i32 s19, s19, 0x8000
	s_waitcnt lgkmcnt(3)
	v_mfma_f32_32x32x16_bf16 v[32:47], v[86:89], v[102:105], v[32:47]
	ds_read_b128 v[86:89], v145 offset:24576
	v_add_f32_e32 v110, v137, v110
	v_add_f32_e32 v110, v138, v110
	v_add_f32_e32 v64, v64, v110
	s_waitcnt lgkmcnt(3)
	v_mfma_f32_32x32x16_bf16 v[48:63], v[98:101], v[102:105], v[48:63]
	ds_read_b128 v[98:101], v145 offset:28672
	s_waitcnt lgkmcnt(3)
	v_mfma_f32_32x32x16_bf16 v[0:15], v[106:109], v[82:85], v[0:15]
	ds_read_b128 v[204:207], v65 offset:16384
	s_waitcnt lgkmcnt(3)
	v_mfma_f32_32x32x16_bf16 v[16:31], v[94:97], v[82:85], v[16:31]
	ds_read_b128 v[208:211], v65 offset:20480
	s_waitcnt lgkmcnt(3)
	v_mfma_f32_32x32x16_bf16 v[32:47], v[86:89], v[82:85], v[32:47]
	ds_read_b128 v[212:215], v65 offset:24576
	s_waitcnt lgkmcnt(3)
	v_mfma_f32_32x32x16_bf16 v[48:63], v[98:101], v[82:85], v[48:63]
	ds_read_b128 v[216:219], v65 offset:28672
	s_add_i32 s17, s18, 3
	s_min_u32 s86, s17, s9
	s_add_i32 s17, s19, 0xffff8000
	s_and_b32 s17, s17, 0x18000
	s_add_i32 s38, s30, s17
	s_lshl_b64 s[20:21], s[86:87], 17
	v_lshl_add_u64 v[82:83], v[164:165], 0, s[20:21]
	s_mov_b32 m0, s38
	s_lshl_b32 s86, s86, 7
	global_load_lds_dwordx4 v[82:83], off
	v_lshl_add_u64 v[82:83], v[82:83], 0, s[14:15]
	s_add_i32 m0, s38, 0x2000
	v_lshl_add_u64 v[84:85], v[166:167], 0, s[86:87]
	global_load_lds_dwordx4 v[82:83], off
	s_add_i32 m0, s38, 0x4000
	s_mov_b32 s17, s87
	global_load_lds_dwordx4 v[84:85], off
	v_lshl_add_u64 v[82:83], v[84:85], 0, s[16:17]
	s_add_i32 m0, s38, 0x6000
	s_cmp_eq_u32 s9, s18
	global_load_lds_dwordx4 v[82:83], off
	s_cbranch_scc1 .LBB0_217
; DI void attn_phase(const bf16_t* __restrict__ qb, const bf16_t* __restrict__ kb, const bf16_t* __restrict__ vt, bf16_t* __restrict__ ob, ...
;     ...
;         for (int kt = 0; kt < nkt; ++kt) {
;             asm volatile("s_waitcnt vmcnt(8)" ::: "memory");
;             asm volatile("s_waitcnt lgkmcnt(0)" ::: "memory"); __builtin_amdgcn_s_barrier();
;             ATT_ISSUE(kt + 3, (kt + 3) & 3);
;             const char* cur = lds + (kt & 3) * 32768;
;             const char* kl = cur + c * 8192; const char* vl = cur + 16384;
;             f32x16 sacc[2];
;             {
;                 bf16x8 kfr[2][4];
; #pragma unroll
;                 for (int kf = 0; kf < 2; ++kf)
; #pragma unroll
;                     for (int s = 0; s < 4; ++s) kfr[kf][s] = ldfrag(kl, kf * 32 + l31, 2 * s + hh);
; #pragma unroll
;                 for (int kf = 0; kf < 2; ++kf) {
;                     sacc[kf] = MFMA(kfr[kf][0], qf[0], negm);
; #pragma unroll
;                     for (int s = 1; s < 4; ++s) sacc[kf] = MFMA(kfr[kf][s], qf[s], sacc[kf]);
;                 }
;             }
;             bf16x8 vf[2][4];
; #pragma unroll
;             for (int ef = 0; ef < 4; ++ef) vf[0][ef] = ldfrag(vl, ef * 32 + l31, hh);
;             __builtin_amdgcn_sched_group_barrier(0x100, 4, 0);
; #pragma unroll
;             for (int g_ = 0; g_ < 4; ++g_) { __builtin_amdgcn_sched_group_barrier(0x008, 1, 0); __builtin_amdgcn_sched_group_barrier(0x100, 1, 0); }
;             __builtin_amdgcn_sched_group_barrier(0x008, 4, 0);
;             __builtin_amdgcn_sched_group_barrier(0x100, 4, 0);
;             float mx = fmaxf(fmaxf(sacc[0][0], sacc[0][1]), sacc[0][2]);
; #pragma unroll
;             for (int i = 3; i < 15; i += 2) mx = fmaxf(fmaxf(mx, sacc[0][i]), sacc[0][i + 1]);
;             mx = fmaxf(fmaxf(mx, sacc[0][15]), sacc[1][0]);
; #pragma unroll
;             for (int i = 1; i < 15; i += 2) mx = fmaxf(fmaxf(mx, sacc[1][i]), sacc[1][i + 1]);
;             mx = fmaxf(mx, sacc[1][15]);
;             if (kt == 0 || __any(mx > 8.0f)) {
;                 const float mfull = fmaxf(mx, __shfl_xor(mx, 32));
;                 const float delta = kt == 0 ? mfull : fmaxf(mfull, 0.f);
;                 const float alpha = kt == 0 ? 1.0f : __builtin_amdgcn_exp2f(-delta);
;                 l_run *= alpha;
; #pragma unroll
;                 for (int ef = 0; ef < 4; ++ef)
; #pragma unroll
.LBB0_215:
	s_waitcnt vmcnt(8)
	s_waitcnt lgkmcnt(0)
	s_barrier
	s_add_i32 s17, s19, 0xfffe8000
	s_and_b32 s17, s17, 0x18000
	s_add_i32 s17, s17, 0
	v_add3_u32 v65, s17, v192, v193
	v_add_u32_e32 v130, v65, v194
	ds_read_b128 v[82:85], v130
	v_add_u32_e32 v134, v65, v198
	ds_read_b128 v[86:89], v134
	v_add_u32_e32 v138, v65, v199
	v_add_u32_e32 v65, v65, v200
	ds_read_b128 v[90:93], v138
	ds_read_b128 v[94:97], v65
	v_mfma_f32_32x32x16_bf16 v[0:15], v[204:207], v[220:223], v[0:15]
	v_mfma_f32_32x32x16_bf16 v[16:31], v[208:211], v[220:223], v[16:31]
	v_mfma_f32_32x32x16_bf16 v[32:47], v[212:215], v[220:223], v[32:47]
	v_mfma_f32_32x32x16_bf16 v[48:63], v[216:219], v[220:223], v[48:63]
	s_waitcnt lgkmcnt(3)
	v_mfma_f32_32x32x16_bf16 v[98:113], v[82:85], v[114:117], v[66:81]
	ds_read_b128 v[130:133], v130 offset:4096
	s_mov_b32 s20, 0x41000000
	s_waitcnt lgkmcnt(3)
	v_mfma_f32_32x32x16_bf16 v[98:113], v[86:89], v[118:121], v[98:113]
	ds_read_b128 v[134:137], v134 offset:4096
	s_waitcnt lgkmcnt(3)
	v_mfma_f32_32x32x16_bf16 v[98:113], v[90:93], v[122:125], v[98:113]
	ds_read_b128 v[138:141], v138 offset:4096
	s_waitcnt lgkmcnt(3)
	v_mfma_f32_32x32x16_bf16 v[98:113], v[94:97], v[126:129], v[98:113]
	ds_read_b128 v[142:145], v65 offset:4096
	v_add3_u32 v65, s17, v194, v193
	s_waitcnt lgkmcnt(3)
	v_mfma_f32_32x32x16_bf16 v[82:97], v[130:133], v[114:117], v[66:81]
	s_nop 7
	v_max_f32_e32 v146, v98, v98
	s_waitcnt lgkmcnt(2)
	v_mfma_f32_32x32x16_bf16 v[82:97], v[134:137], v[118:121], v[82:97]
	s_waitcnt lgkmcnt(1)
	v_mfma_f32_32x32x16_bf16 v[82:97], v[138:141], v[122:125], v[82:97]
	s_waitcnt lgkmcnt(0)
	v_mfma_f32_32x32x16_bf16 v[82:97], v[142:145], v[126:129], v[82:97]
	ds_read_b128 v[142:145], v65 offset:16384
	ds_read_b128 v[138:141], v65 offset:20480
	ds_read_b128 v[134:137], v65 offset:24576
	ds_read_b128 v[130:133], v65 offset:28672
	v_max_f32_e32 v65, v99, v99
	v_max_f32_e32 v65, v146, v65
	v_max3_f32 v65, v65, v100, v101
	v_max3_f32 v65, v65, v102, v103
	v_max3_f32 v65, v65, v104, v105
	v_max3_f32 v65, v65, v106, v107
	v_max3_f32 v65, v65, v108, v109
	v_max3_f32 v65, v65, v110, v111
	v_max3_f32 v65, v65, v112, v113
	v_max3_f32 v65, v65, v82, v83
	v_max3_f32 v65, v65, v84, v85
	v_max3_f32 v65, v65, v86, v87
	v_max3_f32 v65, v65, v88, v89
	v_max3_f32 v65, v65, v90, v91
	v_max3_f32 v65, v65, v92, v93
	v_max3_f32 v65, v65, v94, v95
	v_max3_f32 v65, v65, v96, v97
	v_cmp_lt_f32_e32 vcc, s20, v65
	s_cbranch_vccz .LBB0_214
	ds_bpermute_b32 v146, v190, v65
	s_waitcnt lgkmcnt(0)
	v_max3_f32 v146, v65, v146, 0
	v_exp_f32_e64 v172, -v146
	v_pk_add_f32 v[98:99], v[98:99], v[146:147] op_sel_hi:[1,0] neg_lo:[0,1] neg_hi:[0,1]
	v_pk_add_f32 v[100:101], v[100:101], v[146:147] op_sel_hi:[1,0] neg_lo:[0,1] neg_hi:[0,1]
	v_pk_add_f32 v[102:103], v[102:103], v[146:147] op_sel_hi:[1,0] neg_lo:[0,1] neg_hi:[0,1]
	v_pk_mul_f32 v[14:15], v[14:15], v[172:173] op_sel_hi:[1,0]
	v_pk_mul_f32 v[12:13], v[12:13], v[172:173] op_sel_hi:[1,0]
	v_pk_mul_f32 v[10:11], v[10:11], v[172:173] op_sel_hi:[1,0]
	v_pk_mul_f32 v[8:9], v[8:9], v[172:173] op_sel_hi:[1,0]
	v_pk_mul_f32 v[6:7], v[6:7], v[172:173] op_sel_hi:[1,0]
	v_pk_mul_f32 v[4:5], v[4:5], v[172:173] op_sel_hi:[1,0]
	v_pk_mul_f32 v[2:3], v[2:3], v[172:173] op_sel_hi:[1,0]
	v_pk_mul_f32 v[0:1], v[0:1], v[172:173] op_sel_hi:[1,0]
	v_pk_mul_f32 v[30:31], v[30:31], v[172:173] op_sel_hi:[1,0]
	v_pk_mul_f32 v[28:29], v[28:29], v[172:173] op_sel_hi:[1,0]
	v_pk_mul_f32 v[26:27], v[26:27], v[172:173] op_sel_hi:[1,0]
	v_pk_mul_f32 v[24:25], v[24:25], v[172:173] op_sel_hi:[1,0]
	v_pk_mul_f32 v[22:23], v[22:23], v[172:173] op_sel_hi:[1,0]
	v_pk_mul_f32 v[20:21], v[20:21], v[172:173] op_sel_hi:[1,0]
	v_pk_mul_f32 v[18:19], v[18:19], v[172:173] op_sel_hi:[1,0]
	v_pk_mul_f32 v[16:17], v[16:17], v[172:173] op_sel_hi:[1,0]
	v_pk_mul_f32 v[46:47], v[46:47], v[172:173] op_sel_hi:[1,0]
	v_pk_mul_f32 v[44:45], v[44:45], v[172:173] op_sel_hi:[1,0]
	v_pk_mul_f32 v[42:43], v[42:43], v[172:173] op_sel_hi:[1,0]
	v_pk_mul_f32 v[40:41], v[40:41], v[172:173] op_sel_hi:[1,0]
	v_pk_mul_f32 v[38:39], v[38:39], v[172:173] op_sel_hi:[1,0]
	v_pk_mul_f32 v[36:37], v[36:37], v[172:173] op_sel_hi:[1,0]
	v_pk_mul_f32 v[34:35], v[34:35], v[172:173] op_sel_hi:[1,0]
	v_pk_mul_f32 v[32:33], v[32:33], v[172:173] op_sel_hi:[1,0]
	v_pk_mul_f32 v[62:63], v[62:63], v[172:173] op_sel_hi:[1,0]
	v_pk_mul_f32 v[60:61], v[60:61], v[172:173] op_sel_hi:[1,0]
	v_pk_mul_f32 v[58:59], v[58:59], v[172:173] op_sel_hi:[1,0]
	v_pk_mul_f32 v[56:57], v[56:57], v[172:173] op_sel_hi:[1,0]
	v_pk_mul_f32 v[54:55], v[54:55], v[172:173] op_sel_hi:[1,0]
	v_pk_mul_f32 v[52:53], v[52:53], v[172:173] op_sel_hi:[1,0]
	v_pk_mul_f32 v[50:51], v[50:51], v[172:173] op_sel_hi:[1,0]
	v_pk_mul_f32 v[48:49], v[48:49], v[172:173] op_sel_hi:[1,0]
	v_pk_add_f32 v[104:105], v[104:105], v[146:147] op_sel_hi:[1,0] neg_lo:[0,1] neg_hi:[0,1]
	v_pk_add_f32 v[106:107], v[106:107], v[146:147] op_sel_hi:[1,0] neg_lo:[0,1] neg_hi:[0,1]
	v_pk_add_f32 v[108:109], v[108:109], v[146:147] op_sel_hi:[1,0] neg_lo:[0,1] neg_hi:[0,1]
	v_pk_add_f32 v[110:111], v[110:111], v[146:147] op_sel_hi:[1,0] neg_lo:[0,1] neg_hi:[0,1]
	v_sub_f32_e32 v81, v81, v146
	v_sub_f32_e32 v80, v80, v146
	v_sub_f32_e32 v79, v79, v146
	v_sub_f32_e32 v78, v78, v146
	v_sub_f32_e32 v77, v77, v146
	v_sub_f32_e32 v76, v76, v146
	v_sub_f32_e32 v75, v75, v146
	v_sub_f32_e32 v74, v74, v146
	v_sub_f32_e32 v73, v73, v146
	v_sub_f32_e32 v72, v72, v146
	v_sub_f32_e32 v71, v71, v146
	v_sub_f32_e32 v70, v70, v146
	v_sub_f32_e32 v69, v69, v146
	v_sub_f32_e32 v68, v68, v146
	v_sub_f32_e32 v67, v67, v146
	v_sub_f32_e32 v66, v66, v146
	v_pk_add_f32 v[112:113], v[112:113], v[146:147] op_sel_hi:[1,0] neg_lo:[0,1] neg_hi:[0,1]
	v_sub_f32_e32 v82, v82, v146
	v_sub_f32_e32 v83, v83, v146
	v_sub_f32_e32 v84, v84, v146
	v_sub_f32_e32 v85, v85, v146
	v_sub_f32_e32 v86, v86, v146
	v_sub_f32_e32 v87, v87, v146
	v_sub_f32_e32 v88, v88, v146
	v_sub_f32_e32 v89, v89, v146
	v_sub_f32_e32 v90, v90, v146
	v_sub_f32_e32 v91, v91, v146
	v_sub_f32_e32 v92, v92, v146
	v_sub_f32_e32 v93, v93, v146
	v_sub_f32_e32 v94, v94, v146
	v_sub_f32_e32 v95, v95, v146
	v_sub_f32_e32 v96, v96, v146
	v_sub_f32_e32 v97, v97, v146
	v_mul_f32_e32 v64, v64, v172
	s_branch .LBB0_214
